# v24: + hand-written gather_u main loop (LDS compaction, 4 rows/load, DPP reduce) + hand-written phase-0 weight transposes (16 loads in flight)
# speedup vs baseline: 1.0847x; 1.0513x over previous
; __device__ void transpose_tile(const float* __restrict__ src, int ld_src, int r0, int c0, int c_valid,
;                                bf16_t* __restrict__ dst, int ld_dst, const float* __restrict__ scale, int scale_from,
;                                float* tile, bool valid) {
;   const int tid = threadIdx.x & 255;
;   {
;     const int j = tid & 63, i0 = tid >> 6;
; #pragma unroll
;     for (int ii = 0; ii < 16; ++ii) {
;       const int i = i0 + 4 * ii;
;       float v = 0.f;
;       if (valid && c0 + j < c_valid) {
;         v = src[(size_t)(r0 + i) * ld_src + c0 + j];
;         if (scale != nullptr && (r0 + i) >= scale_from) v *= scale[r0 + i - scale_from];
; __device__ void phase_prep(const Params& p, unsigned char* smem) {
;     ...
;   float* tile = (float*)(smem + hb * SMEM_HALF);
;   const int NT_WIN = 32 * 76, NT_SQ = 32 * 32;
;   const int total = NT_WIN + 2 * NT_SQ + 32;
;   for (int u0 = blockIdx.x * 2; u0 < total; u0 += gridDim.x * 2) {
;     const bool valid = (u0 + hb) < total;
;     const int u = valid ? (u0 + hb) : u0;
;     if (u < NT_WIN) {
;       const int ri = u & 31, cj = u >> 5;
;       transpose_tile(p.w_in, 4624, ri * 64, cj * 64, 4624, (bf16_t*)(ws + OFF_WINT), 2048, p.norm_mix_w, 0, tile, valid);
;     } else if (u < NT_WIN + NT_SQ) {
;       const int v = u - NT_WIN, ri = v & 31, cj = v >> 5;
;       transpose_tile(p.w_out, 2048, ri * 64, cj * 64, 2048, (bf16_t*)(ws + OFF_WOUTT), 2048, p.ssd_norm_w, 1024, tile, valid);
;     } else if (u < NT_WIN + 2 * NT_SQ) {
;       const int v = u - NT_WIN - NT_SQ, ri = v & 31, cj = v >> 5;
;       transpose_tile(p.peer_wq, 2048, ri * 64, cj * 64, 2048, (bf16_t*)(ws + OFF_WQT), 2048, p.norm_ffn_w, 0, tile, valid);
;     } else {
;       const int v = u - NT_WIN - 2 * NT_SQ;
;       const int h = v & 15;
;       const float* src = (v < 16 ? p.lru_wa : p.lru_wx) + (size_t)h * 4096;
;       bf16_t* dst = (bf16_t*)(ws + (v < 16 ? OFF_WAT : OFF_WXT)) + (size_t)h * 4096;
;       transpose_tile(src, 64, 0, 0, 64, dst, 64, nullptr, 0, tile, valid);
;     }
;   }
.LBB0_11:
	s_or_b64 exec, exec, s[4:5]
	s_lshl_b32 s33, s2, 1
	s_cmpk_gt_i32 s33, 0x119f
	s_movk_i32 s71, 0x119f
	s_cbranch_scc1 .LBB0_253
	v_and_b32_e32 v1, 0xff, v139
	v_and_b32_e32 v2, 63, v139
	v_lshrrev_b32_e32 v5, 6, v1
	v_lshlrev_b32_e32 v6, 2, v2
	v_mul_u32_u24_e32 v7, 0x104, v5
	v_and_b32_e32 v8, 15, v1
	v_lshrrev_b32_e32 v9, 4, v1
	v_add3_u32 v7, v7, v6, v166
	v_mul_u32_u24_e32 v10, 0x410, v8
	v_lshlrev_b32_e32 v12, 2, v9
	v_add3_u32 v10, v10, v12, v166
	v_lshlrev_b32_e32 v8, 3, v8
	v_mov_b32_e32 v50, 0
	v_readfirstlane_b32 s77, v165
	v_readfirstlane_b32 s78, v5
	s_lshl_b32 s0, s2, 1
	s_lshl_b32 s79, s96, 1
.Ltp_loop:
	s_add_i32 s1, s0, s77
	s_cmpk_lt_i32 s1, 0x11a0
	s_cselect_b32 s73, 1, 0
	s_cselect_b32 s1, s1, s0
	s_cmpk_lt_i32 s1, 0x980
	s_cbranch_scc1 .Ltp_c0
	s_cmpk_lt_i32 s1, 0xd80
	s_cbranch_scc1 .Ltp_c1
	s_cmpk_lt_i32 s1, 0x1180
	s_cbranch_scc1 .Ltp_c2
	s_sub_i32 s3, s1, 0x1180
	s_and_b32 s4, s3, 15
	s_cmp_lt_i32 s3, 16
	s_cselect_b32 s82, s46, s50
	s_cselect_b32 s83, s47, s51
	s_mov_b32 s84, 0x1d720000
	s_cselect_b32 s84, 0x1d700000, s84
	s_lshl_b32 s5, s4, 14
	s_add_u32 s82, s82, s5
	s_addc_u32 s83, s83, 0
	s_lshl_b32 s5, s4, 13
	s_add_u32 s84, s84, s5
	s_add_u32 s10, s34, s84
	s_addc_u32 s11, s35, 0
	s_movk_i32 s85, 64
	s_movk_i32 s12, 0x80
	s_movk_i32 s72, 64
	s_mov_b32 s13, 0
	s_branch .Ltp_go
.Ltp_c0:
	s_mov_b32 s3, s1
	s_mov_b64 s[82:83], s[40:41]
	s_movk_i32 s85, 0x1210
	s_movk_i32 s86, 0x1210
	s_mov_b32 s84, 0x1b400000
	s_mov_b64 s[70:71], s[38:39]
	s_mov_b32 s87, 0
	s_branch .Ltp_sq
.Ltp_c1:
	s_sub_i32 s3, s1, 0x980
	s_mov_b64 s[82:83], s[16:17]
	s_movk_i32 s85, 0x800
	s_movk_i32 s86, 0x800
	s_mov_b32 s84, 0x1c700000
	s_mov_b64 s[70:71], s[66:67]
	s_movk_i32 s87, 0x400
	s_branch .Ltp_sq
.Ltp_c2:
	s_sub_i32 s3, s1, 0xd80
	s_mov_b64 s[82:83], s[20:21]
	s_movk_i32 s85, 0x800
	s_movk_i32 s86, 0x800
	s_mov_b32 s84, 0x1cf00000
	s_mov_b64 s[70:71], s[18:19]
	s_mov_b32 s87, 0
.Ltp_sq:
	s_and_b32 s4, s3, 31
	s_lshr_b32 s5, s3, 5
	s_lshl_b32 s4, s4, 6
	s_lshl_b32 s5, s5, 6
	s_sub_i32 s72, s86, s5
	s_mul_i32 s6, s4, s85
	s_add_i32 s6, s6, s5
	s_lshl_b32 s6, s6, 2
	s_add_u32 s82, s82, s6
	s_addc_u32 s83, s83, 0
	s_lshl_b32 s6, s5, 12
	s_lshl_b32 s7, s4, 1
	s_add_u32 s6, s6, s7
	s_add_u32 s6, s6, s84
	s_add_u32 s10, s34, s6
	s_addc_u32 s11, s35, 0
	s_movk_i32 s12, 0x1000
	s_sub_i32 s7, s4, s87
	s_cmp_ge_i32 s7, 0
	s_cselect_b32 s13, 1, 0
	s_max_i32 s7, s7, 0
	s_lshl_b32 s7, s7, 2
	s_add_u32 s70, s70, s7
	s_addc_u32 s71, s71, 0
; __device__ void transpose_tile(const float* __restrict__ src, int ld_src, int r0, int c0, int c_valid,
;                                bf16_t* __restrict__ dst, int ld_dst, const float* __restrict__ scale, int scale_from,
;                                float* tile, bool valid) {
;   const int tid = threadIdx.x & 255;
;   {
;     const int j = tid & 63, i0 = tid >> 6;
; #pragma unroll
;     for (int ii = 0; ii < 16; ++ii) {
;       const int i = i0 + 4 * ii;
;       float v = 0.f;
;       if (valid && c0 + j < c_valid) {
;         v = src[(size_t)(r0 + i) * ld_src + c0 + j];
;         if (scale != nullptr && (r0 + i) >= scale_from) v *= scale[r0 + i - scale_from];
;       }
;       tile[i * 65 + j] = v;
;     }
;   }
;   __syncthreads();
;   {
;     const int i4 = tid & 15, j0 = tid >> 4;
; #pragma unroll
;     for (int jj = 0; jj < 4; ++jj) {
;       const int j = j0 + 16 * jj;
;       const float* tp = tile + (4 * i4) * 65 + j;
;       u32x2 o = {pk2(tp[0], tp[65]), pk2(tp[130], tp[195])};
;       if (valid) *(u32x2*)(dst + (size_t)(c0 + j) * ld_dst + r0 + 4 * i4) = o;
;     }
;   }
;   __syncthreads();
.Ltp_go:
	s_mul_i32 s6, s78, s85
	s_lshl_b32 s6, s6, 2
	s_add_u32 s6, s82, s6
	s_addc_u32 s7, s83, 0
	s_lshl_b32 s8, s85, 4
	s_lshl_b32 s9, s78, 2
	s_add_u32 s70, s70, s9
	s_addc_u32 s71, s71, 0
	v_mov_b32_e32 v18, 0
	v_mov_b32_e32 v19, 0
	v_mov_b32_e32 v20, 0
	v_mov_b32_e32 v21, 0
	v_mov_b32_e32 v22, 0
	v_mov_b32_e32 v23, 0
	v_mov_b32_e32 v24, 0
	v_mov_b32_e32 v25, 0
	v_mov_b32_e32 v26, 0
	v_mov_b32_e32 v27, 0
	v_mov_b32_e32 v28, 0
	v_mov_b32_e32 v29, 0
	v_mov_b32_e32 v30, 0
	v_mov_b32_e32 v31, 0
	v_mov_b32_e32 v32, 0
	v_mov_b32_e32 v33, 0
	v_cmp_gt_i32_e64 s[74:75], s72, v2
	s_cmp_eq_u32 s73, 0
	s_cbranch_scc1 .Ltp_noload
	s_mov_b64 s[80:81], exec
	s_and_b64 exec, exec, s[74:75]
	s_cbranch_execz .Ltp_ldone
	global_load_dword v18, v6, s[6:7]
	s_add_u32 s6, s6, s8
	s_addc_u32 s7, s7, 0
	global_load_dword v19, v6, s[6:7]
	s_add_u32 s6, s6, s8
	s_addc_u32 s7, s7, 0
	global_load_dword v20, v6, s[6:7]
	s_add_u32 s6, s6, s8
	s_addc_u32 s7, s7, 0
	global_load_dword v21, v6, s[6:7]
	s_add_u32 s6, s6, s8
	s_addc_u32 s7, s7, 0
	global_load_dword v22, v6, s[6:7]
	s_add_u32 s6, s6, s8
	s_addc_u32 s7, s7, 0
	global_load_dword v23, v6, s[6:7]
	s_add_u32 s6, s6, s8
	s_addc_u32 s7, s7, 0
	global_load_dword v24, v6, s[6:7]
	s_add_u32 s6, s6, s8
	s_addc_u32 s7, s7, 0
	global_load_dword v25, v6, s[6:7]
	s_add_u32 s6, s6, s8
	s_addc_u32 s7, s7, 0
	global_load_dword v26, v6, s[6:7]
	s_add_u32 s6, s6, s8
	s_addc_u32 s7, s7, 0
	global_load_dword v27, v6, s[6:7]
	s_add_u32 s6, s6, s8
	s_addc_u32 s7, s7, 0
	global_load_dword v28, v6, s[6:7]
	s_add_u32 s6, s6, s8
	s_addc_u32 s7, s7, 0
	global_load_dword v29, v6, s[6:7]
	s_add_u32 s6, s6, s8
	s_addc_u32 s7, s7, 0
	global_load_dword v30, v6, s[6:7]
	s_add_u32 s6, s6, s8
	s_addc_u32 s7, s7, 0
	global_load_dword v31, v6, s[6:7]
	s_add_u32 s6, s6, s8
	s_addc_u32 s7, s7, 0
	global_load_dword v32, v6, s[6:7]
	s_add_u32 s6, s6, s8
	s_addc_u32 s7, s7, 0
	global_load_dword v33, v6, s[6:7]
	s_cmp_eq_u32 s13, 0
	s_cbranch_scc1 .Ltp_ldone
	global_load_dword v34, v50, s[70:71]
	global_load_dword v35, v50, s[70:71] offset:16
	global_load_dword v36, v50, s[70:71] offset:32
	global_load_dword v37, v50, s[70:71] offset:48
	global_load_dword v38, v50, s[70:71] offset:64
	global_load_dword v39, v50, s[70:71] offset:80
	global_load_dword v40, v50, s[70:71] offset:96
	global_load_dword v41, v50, s[70:71] offset:112
	global_load_dword v42, v50, s[70:71] offset:128
	global_load_dword v43, v50, s[70:71] offset:144
	global_load_dword v44, v50, s[70:71] offset:160
	global_load_dword v45, v50, s[70:71] offset:176
	global_load_dword v46, v50, s[70:71] offset:192
	global_load_dword v47, v50, s[70:71] offset:208
	global_load_dword v48, v50, s[70:71] offset:224
	global_load_dword v49, v50, s[70:71] offset:240
	s_waitcnt vmcnt(0)
	v_mul_f32_e32 v18, v18, v34
	v_mul_f32_e32 v19, v19, v35
	v_mul_f32_e32 v20, v20, v36
	v_mul_f32_e32 v21, v21, v37
	v_mul_f32_e32 v22, v22, v38
	v_mul_f32_e32 v23, v23, v39
	v_mul_f32_e32 v24, v24, v40
	v_mul_f32_e32 v25, v25, v41
	v_mul_f32_e32 v26, v26, v42
	v_mul_f32_e32 v27, v27, v43
	v_mul_f32_e32 v28, v28, v44
	v_mul_f32_e32 v29, v29, v45
	v_mul_f32_e32 v30, v30, v46
	v_mul_f32_e32 v31, v31, v47
	v_mul_f32_e32 v32, v32, v48
	v_mul_f32_e32 v33, v33, v49
.Ltp_ldone:
	s_mov_b64 exec, s[80:81]
.Ltp_noload:
	s_waitcnt vmcnt(0)
	ds_write_b32 v7, v18
	ds_write_b32 v7, v19 offset:1040
	ds_write_b32 v7, v20 offset:2080
	ds_write_b32 v7, v21 offset:3120
	ds_write_b32 v7, v22 offset:4160
	ds_write_b32 v7, v23 offset:5200
	ds_write_b32 v7, v24 offset:6240
	ds_write_b32 v7, v25 offset:7280
	ds_write_b32 v7, v26 offset:8320
	ds_write_b32 v7, v27 offset:9360
	ds_write_b32 v7, v28 offset:10400
	ds_write_b32 v7, v29 offset:11440
	ds_write_b32 v7, v30 offset:12480
	ds_write_b32 v7, v31 offset:13520
	ds_write_b32 v7, v32 offset:14560
	ds_write_b32 v7, v33 offset:15600
	s_waitcnt lgkmcnt(0)
	s_barrier
	v_mul_u32_u24_e32 v12, s12, v9
	v_add_u32_e32 v12, v12, v8
	s_lshl_b32 s9, s12, 4
	ds_read2_b32 v[52:53], v10 offset0:0 offset1:65
	ds_read2_b32 v[54:55], v10 offset0:130 offset1:195
	ds_read2_b32 v[56:57], v10 offset0:16 offset1:81
	ds_read2_b32 v[58:59], v10 offset0:146 offset1:211
	ds_read2_b32 v[60:61], v10 offset0:32 offset1:97
	ds_read2_b32 v[62:63], v10 offset0:162 offset1:227
	ds_read2_b32 v[64:65], v10 offset0:48 offset1:113
	ds_read2_b32 v[66:67], v10 offset0:178 offset1:243
	s_waitcnt lgkmcnt(0)
	v_cvt_pk_bf16_f32 v52, v52, v53
	v_cvt_pk_bf16_f32 v53, v54, v55
	v_cvt_pk_bf16_f32 v56, v56, v57
	v_cvt_pk_bf16_f32 v57, v58, v59
	v_cvt_pk_bf16_f32 v60, v60, v61
	v_cvt_pk_bf16_f32 v61, v62, v63
	v_cvt_pk_bf16_f32 v64, v64, v65
	v_cvt_pk_bf16_f32 v65, v66, v67
	s_cmp_eq_u32 s73, 0
	s_cbranch_scc1 .Ltp_nostore
	global_store_dwordx2 v12, v[52:53], s[10:11]
	s_add_u32 s10, s10, s9
	s_addc_u32 s11, s11, 0
	global_store_dwordx2 v12, v[56:57], s[10:11]
	s_add_u32 s10, s10, s9
	s_addc_u32 s11, s11, 0
	global_store_dwordx2 v12, v[60:61], s[10:11]
	s_add_u32 s10, s10, s9
	s_addc_u32 s11, s11, 0
	global_store_dwordx2 v12, v[64:65], s[10:11]
.Ltp_nostore:
	s_barrier
	s_add_i32 s0, s0, s79
	s_cmpk_lt_i32 s0, 0x11a0
	s_cbranch_scc1 .Ltp_loop

; __device__ void phase_gather_u(const Params& p) {
;     ...
; #pragma unroll 1
;   for (int r = 0; r < 4; ++r) {
; #pragma unroll 1
;     for (int t = tbase; t < T_TOK; t += tstride) {
;       const u32x4 ph = xq[((size_t)t * 64 + lane) * 2], pl = xq[((size_t)t * 64 + lane) * 2 + 1];
;       const int idA = idxg[(size_t)t * 128 + lane], idB = idxg[(size_t)t * 128 + 64 + lane];
;       unsigned long long m0 = __ballot((idA >> 12) == r), m1 = __ballot((idB >> 12) == r);
;       while (m0 | m1) {
;         int jk[16];
;         u32x4 rw[16];
;         const int nvalid = min((int)(__popcll(m0) + __popcll(m1)), 16);
;         int jfirst, efirst;
;         if (m0) { jfirst = __builtin_amdgcn_readfirstlane(__ffsll((long long)m0) - 1); efirst = __builtin_amdgcn_readlane(idA, jfirst); }
;         else { const int j1 = __builtin_amdgcn_readfirstlane(__ffsll((long long)m1) - 1); efirst = __builtin_amdgcn_readlane(idB, j1); jfirst = 64 + j1; }
; #pragma unroll
;         for (int k = 0; k < 16; ++k) {
;           int j = jfirst, e = efirst;
;           if (m0) { const int jj = __builtin_amdgcn_readfirstlane(__ffsll((long long)m0) - 1); m0 &= m0 - 1ull; j = jj; e = __builtin_amdgcn_readlane(idA, jj); }
;           else if (m1) { const int jj = __builtin_amdgcn_readfirstlane(__ffsll((long long)m1) - 1); m1 &= m1 - 1ull; j = 64 + jj; e = __builtin_amdgcn_readlane(idB, jj); }
;           jk[k] = j;
;           rw[k] = *(const u32x4*)(ub + (size_t)e * 1024 + lane * 16);
;         }
.LBB0_1205:
	s_or_b64 exec, exec, s[4:5]
	v_and_b32_e32 v0, 32, v139
	v_cmp_eq_u32_e64 s[2:3], 0, v0
	v_and_b32_e32 v0, 16, v139
	v_cmp_eq_u32_e64 s[4:5], 0, v0
	v_and_b32_e32 v0, 8, v139
	s_add_u32 s10, s34, 0xc000000
	v_cmp_eq_u32_e64 s[6:7], 0, v0
	v_mov_b32_e32 v1, 0
	v_lshlrev_b32_e32 v0, 5, v138
	s_addc_u32 s11, s35, 0
	s_waitcnt lgkmcnt(0)
	v_lshl_add_u64 v[2:3], s[34:35], 0, v[0:1]
	v_lshlrev_b32_e32 v0, 2, v138
	v_lshlrev_b32_e32 v82, 3, v139
	v_writelane_b32 v250, s10, 18
	v_mbcnt_hi_u32_b32 v83, -1, v30
	v_and_b32_e32 v4, 56, v82
	v_lshl_add_u64 v[76:77], s[10:11], 0, v[0:1]
	v_lshlrev_b32_e32 v0, 4, v138
	s_waitcnt vmcnt(0)
	v_lshl_add_u64 v[72:73], s[34:35], 0, v[0:1]
	v_and_b32_e32 v0, 64, v83
	s_add_u32 s70, s34, 0x17400000
	s_mov_b64 s[8:9], 0x15400000
	v_add_u32_e32 v84, 64, v0
	v_or_b32_e32 v0, v0, v4
	s_addc_u32 s71, s35, 0
	s_mov_b32 s33, 0
	v_lshl_add_u64 v[74:75], v[2:3], 0, s[8:9]
	v_writelane_b32 v250, s11, 19
	v_cmp_gt_u32_e64 s[8:9], 8, v138
	v_cmp_eq_u32_e64 s[10:11], 1, v138
	v_cmp_eq_u32_e64 s[12:13], 2, v138
	v_cmp_eq_u32_e64 s[14:15], 3, v138
	v_cmp_eq_u32_e64 s[16:17], 4, v138
	v_cmp_eq_u32_e64 s[18:19], 5, v138
	v_cmp_eq_u32_e64 s[20:21], 6, v138
	v_cmp_eq_u32_e64 s[22:23], 7, v138
	s_movk_i32 s48, 0x3fff
	v_xor_b32_e32 v89, 32, v83
	v_xor_b32_e32 v90, 16, v83
	v_xor_b32_e32 v88, 8, v83
	v_xor_b32_e32 v87, 4, v83
	v_xor_b32_e32 v86, 2, v83
	v_xor_b32_e32 v85, 1, v83
	v_lshlrev_b32_e32 v91, 2, v0
	v_and_b32_e32 v96, 15, v138
	v_lshrrev_b32_e32 v99, 4, v138
	v_lshlrev_b32_e32 v98, 2, v138
	v_lshrrev_b32_e32 v100, 6, v139
	v_cmp_eq_u32_e64 s[8:9], 0, v96
	v_lshlrev_b32_e32 v97, 5, v96
	v_lshlrev_b32_e32 v96, 4, v96
	v_readfirstlane_b32 s60, v100
	v_readfirstlane_b32 s61, v112
	s_add_u32 s64, s34, 0x15400000
	s_addc_u32 s65, s35, 0
	s_add_u32 s62, s34, 0xc000000
	s_addc_u32 s63, s35, 0
	s_lshl_b32 s60, s60, 10
	s_and_saveexec_b64 s[38:39], s[0:1]
	s_cbranch_execz .Lgu_done
	s_mov_b32 s33, 0
.Lgu_rloop:
	s_mov_b32 s36, s61
	s_lshl_b32 s37, s36, 9
	s_add_u32 s40, s62, s37
	s_addc_u32 s41, s63, 0
	global_load_dword v94, v98, s[40:41]
	global_load_dword v95, v98, s[40:41] offset:256
.Lgu_tloop:
	s_lshl_b32 s37, s36, 11
	s_add_u32 s46, s64, s37
	s_addc_u32 s47, s65, 0
	s_lshl_b32 s37, s36, 9
	s_add_u32 s48, s70, s37
	s_addc_u32 s49, s71, 0
	global_load_dwordx4 v[0:3], v97, s[46:47]
	global_load_dwordx4 v[4:7], v97, s[46:47] offset:16
	global_load_dwordx4 v[8:11], v97, s[46:47] offset:512
	global_load_dwordx4 v[12:15], v97, s[46:47] offset:528
	global_load_dwordx4 v[16:19], v97, s[46:47] offset:1024
	global_load_dwordx4 v[20:23], v97, s[46:47] offset:1040
	global_load_dwordx4 v[24:27], v97, s[46:47] offset:1536
	global_load_dwordx4 v[28:31], v97, s[46:47] offset:1552
	s_add_i32 s37, s36, s68
	s_cmp_gt_i32 s37, 0x3fff
	s_cselect_b32 s37, s61, s37
	s_lshl_b32 s37, s37, 9
	s_add_u32 s40, s62, s37
	s_addc_u32 s41, s63, 0
	s_waitcnt vmcnt(8)
	v_mov_b32_e32 v92, v94
	v_mov_b32_e32 v93, v95
	s_nop 1
	global_load_dword v94, v98, s[40:41]
	global_load_dword v95, v98, s[40:41] offset:256
	v_lshrrev_b32_e32 v103, 12, v92
	v_lshrrev_b32_e32 v104, 12, v93
	v_cmp_eq_u32_e64 s[44:45], s33, v103
	v_cmp_eq_u32_e64 s[42:43], s33, v104
	s_nop 3
	s_bcnt1_i32_b64 s59, s[44:45]
	s_bcnt1_i32_b64 s56, s[42:43]
	s_add_i32 s56, s56, s59
	s_cmp_eq_u32 s56, 0
	s_cbranch_scc1 .Lgu_tnext
	v_mbcnt_lo_u32_b32 v114, s44, 0
	v_mbcnt_hi_u32_b32 v114, s45, v114
	v_mbcnt_lo_u32_b32 v111, s42, 0
	v_mbcnt_hi_u32_b32 v111, s43, v111
	v_lshl_add_u32 v113, v92, 8, v138
	v_lshl_add_u32 v100, v114, 2, s60
	v_add_u32_e32 v111, s59, v111
	s_mov_b64 exec, s[44:45]
	ds_write_b32 v100, v113
	s_mov_b64 exec, -1
	v_add_u32_e32 v113, 64, v138
	v_lshl_add_u32 v100, v111, 2, s60
	v_lshl_add_u32 v113, v93, 8, v113
	s_mov_b64 exec, s[42:43]
	ds_write_b32 v100, v113
	s_mov_b64 exec, -1
	s_add_i32 s57, s56, 3
	s_lshr_b32 s57, s57, 2
	v_lshl_add_u32 v101, v99, 2, s60
	v_mov_b32_e32 v102, v99
	s_mov_b32 s58, 0
	ds_read_b32 v115, v101
	v_add_u32_e32 v101, 16, v101
	s_waitcnt lgkmcnt(0)
	v_mov_b32_e32 v103, v115
	ds_read_b32 v115, v101
	v_cmp_gt_u32_e64 s[50:51], s56, v102
	v_add_u32_e32 v101, 16, v101
	v_add_u32_e32 v102, 4, v102
	s_nop 0
	v_cndmask_b32_e64 v103, 0, v103, s[50:51]
	v_and_b32_e32 v104, 0xffffff00, v103
	v_and_b32_e32 v105, 0xff, v103
	v_lshl_add_u32 v104, v104, 2, v96
	v_lshlrev_b32_e32 v105, 2, v105
	s_and_b64 s[50:51], s[50:51], s[8:9]
	global_load_dwordx4 v[32:35], v104, s[34:35]
	global_load_dwordx4 v[36:39], v104, s[34:35] offset:256
	global_load_dwordx4 v[40:43], v104, s[34:35] offset:512
	global_load_dwordx4 v[44:47], v104, s[34:35] offset:768
	s_waitcnt lgkmcnt(0)
	v_mov_b32_e32 v103, v115
	ds_read_b32 v115, v101
	v_cmp_gt_u32_e64 s[52:53], s56, v102
	v_add_u32_e32 v101, 16, v101
	v_add_u32_e32 v102, 4, v102
	s_nop 0
	v_cndmask_b32_e64 v103, 0, v103, s[52:53]
	v_and_b32_e32 v104, 0xffffff00, v103
	v_and_b32_e32 v106, 0xff, v103
	v_lshl_add_u32 v104, v104, 2, v96
	v_lshlrev_b32_e32 v106, 2, v106
	s_and_b64 s[52:53], s[52:53], s[8:9]
	global_load_dwordx4 v[48:51], v104, s[34:35]
	global_load_dwordx4 v[52:55], v104, s[34:35] offset:256
	global_load_dwordx4 v[56:59], v104, s[34:35] offset:512
	global_load_dwordx4 v[60:63], v104, s[34:35] offset:768
; __device__ void phase_gather_u(const Params& p) {
;     ...
; #pragma unroll
;         for (int k = 0; k < 16; ++k) {
;           int j = jfirst, e = efirst;
;           if (m0) { const int jj = __builtin_amdgcn_readfirstlane(__ffsll((long long)m0) - 1); m0 &= m0 - 1ull; j = jj; e = __builtin_amdgcn_readlane(idA, jj); }
;           else if (m1) { const int jj = __builtin_amdgcn_readfirstlane(__ffsll((long long)m1) - 1); m1 &= m1 - 1ull; j = 64 + jj; e = __builtin_amdgcn_readlane(idB, jj); }
;           jk[k] = j;
;           rw[k] = *(const u32x4*)(ub + (size_t)e * 1024 + lane * 16);
;         }
; #pragma unroll
;         for (int bt = 0; bt < 2; ++bt) {
;           int dv[8];
; #pragma unroll
;           for (int k = 0; k < 8; ++k) {
;             int dh = 0, dl = 0;
; #pragma unroll
;             for (int q = 0; q < 4; ++q) {
;               dh = __builtin_amdgcn_sdot8((int)rw[bt * 8 + k][q], (int)ph[q], dh, false);
;               dl = __builtin_amdgcn_sdot8((int)rw[bt * 8 + k][q], (int)pl[q], dl, false);
;             }
;             dv[k] = 16 * dh + dl;
;           }
;           int a4[4], a2[2];
; #pragma unroll
;           for (int k = 0; k < 4; ++k) {
;             const int mine = b5 ? dv[k + 4] : dv[k], oth = b5 ? dv[k] : dv[k + 4];
;             a4[k] = mine + __shfl_xor(oth, 32);
;           }
; #pragma unroll
;           for (int k = 0; k < 2; ++k) {
;             const int mine = b4 ? a4[k + 2] : a4[k], oth = b4 ? a4[k] : a4[k + 2];
;             a2[k] = mine + __shfl_xor(oth, 16);
;           }
;           int c1;
;           {
;             const int mine = b3 ? a2[1] : a2[0], oth = b3 ? a2[0] : a2[1];
;             c1 = mine + __shfl_xor(oth, 8);
;           }
;           c1 += __shfl_xor(c1, 4);
;           c1 += __shfl_xor(c1, 2);
;           c1 += __shfl_xor(c1, 1);
;           const int val = __shfl(c1, srcl);
;           int jsel = jk[bt * 8];
; #pragma unroll
;           for (int k = 1; k < 8; ++k) jsel = (lane == k) ? jk[bt * 8 + k] : jsel;
;           if (lane < 8 && lane < nvalid - bt * 8) wbuf[(size_t)t * 128 + jsel] = val;
.Lgu_gloop:
	s_waitcnt lgkmcnt(0)
	v_mov_b32_e32 v103, v115
	ds_read_b32 v115, v101
	v_cmp_gt_u32_e64 s[54:55], s56, v102
	v_add_u32_e32 v101, 16, v101
	v_add_u32_e32 v102, 4, v102
	s_nop 0
	v_cndmask_b32_e64 v103, 0, v103, s[54:55]
	v_and_b32_e32 v104, 0xffffff00, v103
	v_and_b32_e32 v107, 0xff, v103
	v_lshl_add_u32 v104, v104, 2, v96
	v_lshlrev_b32_e32 v107, 2, v107
	s_and_b64 s[54:55], s[54:55], s[8:9]
	global_load_dwordx4 v[144:147], v104, s[34:35]
	global_load_dwordx4 v[148:151], v104, s[34:35] offset:256
	global_load_dwordx4 v[152:155], v104, s[34:35] offset:512
	global_load_dwordx4 v[156:159], v104, s[34:35] offset:768
	s_waitcnt vmcnt(8)
	v_mov_b32_e32 v108, 0
	v_mov_b32_e32 v109, 0
	s_nop 1
	v_dot8c_i32_i4_e32 v108, v32, v0
	v_dot8c_i32_i4_e32 v109, v32, v4
	v_dot8c_i32_i4_e32 v108, v33, v1
	v_dot8c_i32_i4_e32 v109, v33, v5
	v_dot8c_i32_i4_e32 v108, v34, v2
	v_dot8c_i32_i4_e32 v109, v34, v6
	v_dot8c_i32_i4_e32 v108, v35, v3
	v_dot8c_i32_i4_e32 v109, v35, v7
	v_dot8c_i32_i4_e32 v108, v36, v8
	v_dot8c_i32_i4_e32 v109, v36, v12
	v_dot8c_i32_i4_e32 v108, v37, v9
	v_dot8c_i32_i4_e32 v109, v37, v13
	v_dot8c_i32_i4_e32 v108, v38, v10
	v_dot8c_i32_i4_e32 v109, v38, v14
	v_dot8c_i32_i4_e32 v108, v39, v11
	v_dot8c_i32_i4_e32 v109, v39, v15
	v_dot8c_i32_i4_e32 v108, v40, v16
	v_dot8c_i32_i4_e32 v109, v40, v20
	v_dot8c_i32_i4_e32 v108, v41, v17
	v_dot8c_i32_i4_e32 v109, v41, v21
	v_dot8c_i32_i4_e32 v108, v42, v18
	v_dot8c_i32_i4_e32 v109, v42, v22
	v_dot8c_i32_i4_e32 v108, v43, v19
	v_dot8c_i32_i4_e32 v109, v43, v23
	v_dot8c_i32_i4_e32 v108, v44, v24
	v_dot8c_i32_i4_e32 v109, v44, v28
	v_dot8c_i32_i4_e32 v108, v45, v25
	v_dot8c_i32_i4_e32 v109, v45, v29
	v_dot8c_i32_i4_e32 v108, v46, v26
	v_dot8c_i32_i4_e32 v109, v46, v30
	v_dot8c_i32_i4_e32 v108, v47, v27
	v_dot8c_i32_i4_e32 v109, v47, v31
	s_nop 2
	v_lshl_add_u32 v110, v108, 4, v109
	s_nop 1
	v_add_u32_dpp v110, v110, v110 quad_perm:[1,0,3,2] row_mask:0xf bank_mask:0xf
	s_nop 1
	v_add_u32_dpp v110, v110, v110 quad_perm:[2,3,0,1] row_mask:0xf bank_mask:0xf
	s_nop 1
	v_add_u32_dpp v110, v110, v110 row_half_mirror row_mask:0xf bank_mask:0xf
	s_nop 1
	v_add_u32_dpp v110, v110, v110 row_mirror row_mask:0xf bank_mask:0xf
	s_mov_b64 exec, s[50:51]
	global_store_dword v105, v110, s[48:49]
	s_mov_b64 exec, -1
	s_add_i32 s58, s58, 1
	s_cmp_ge_u32 s58, s57
	s_cbranch_scc1 .Lgu_tnext
	s_waitcnt lgkmcnt(0)
	v_mov_b32_e32 v103, v115
	ds_read_b32 v115, v101
	v_cmp_gt_u32_e64 s[50:51], s56, v102
	v_add_u32_e32 v101, 16, v101
	v_add_u32_e32 v102, 4, v102
	s_nop 0
	v_cndmask_b32_e64 v103, 0, v103, s[50:51]
	v_and_b32_e32 v104, 0xffffff00, v103
	v_and_b32_e32 v105, 0xff, v103
	v_lshl_add_u32 v104, v104, 2, v96
	v_lshlrev_b32_e32 v105, 2, v105
	s_and_b64 s[50:51], s[50:51], s[8:9]
	global_load_dwordx4 v[32:35], v104, s[34:35]
	global_load_dwordx4 v[36:39], v104, s[34:35] offset:256
	global_load_dwordx4 v[40:43], v104, s[34:35] offset:512
	global_load_dwordx4 v[44:47], v104, s[34:35] offset:768
	s_waitcnt vmcnt(8)
	v_mov_b32_e32 v108, 0
	v_mov_b32_e32 v109, 0
	s_nop 1
	v_dot8c_i32_i4_e32 v108, v48, v0
	v_dot8c_i32_i4_e32 v109, v48, v4
	v_dot8c_i32_i4_e32 v108, v49, v1
	v_dot8c_i32_i4_e32 v109, v49, v5
	v_dot8c_i32_i4_e32 v108, v50, v2
	v_dot8c_i32_i4_e32 v109, v50, v6
	v_dot8c_i32_i4_e32 v108, v51, v3
	v_dot8c_i32_i4_e32 v109, v51, v7
	v_dot8c_i32_i4_e32 v108, v52, v8
	v_dot8c_i32_i4_e32 v109, v52, v12
	v_dot8c_i32_i4_e32 v108, v53, v9
	v_dot8c_i32_i4_e32 v109, v53, v13
	v_dot8c_i32_i4_e32 v108, v54, v10
	v_dot8c_i32_i4_e32 v109, v54, v14
	v_dot8c_i32_i4_e32 v108, v55, v11
	v_dot8c_i32_i4_e32 v109, v55, v15
	v_dot8c_i32_i4_e32 v108, v56, v16
	v_dot8c_i32_i4_e32 v109, v56, v20
	v_dot8c_i32_i4_e32 v108, v57, v17
	v_dot8c_i32_i4_e32 v109, v57, v21
	v_dot8c_i32_i4_e32 v108, v58, v18
	v_dot8c_i32_i4_e32 v109, v58, v22
	v_dot8c_i32_i4_e32 v108, v59, v19
	v_dot8c_i32_i4_e32 v109, v59, v23
	v_dot8c_i32_i4_e32 v108, v60, v24
	v_dot8c_i32_i4_e32 v109, v60, v28
	v_dot8c_i32_i4_e32 v108, v61, v25
	v_dot8c_i32_i4_e32 v109, v61, v29
	v_dot8c_i32_i4_e32 v108, v62, v26
	v_dot8c_i32_i4_e32 v109, v62, v30
	v_dot8c_i32_i4_e32 v108, v63, v27
	v_dot8c_i32_i4_e32 v109, v63, v31
	s_nop 2
	v_lshl_add_u32 v110, v108, 4, v109
	s_nop 1
	v_add_u32_dpp v110, v110, v110 quad_perm:[1,0,3,2] row_mask:0xf bank_mask:0xf
	s_nop 1
	v_add_u32_dpp v110, v110, v110 quad_perm:[2,3,0,1] row_mask:0xf bank_mask:0xf
	s_nop 1
	v_add_u32_dpp v110, v110, v110 row_half_mirror row_mask:0xf bank_mask:0xf
	s_nop 1
	v_add_u32_dpp v110, v110, v110 row_mirror row_mask:0xf bank_mask:0xf
	s_mov_b64 exec, s[52:53]
	global_store_dword v106, v110, s[48:49]
	s_mov_b64 exec, -1
	s_add_i32 s58, s58, 1
	s_cmp_ge_u32 s58, s57
	s_cbranch_scc1 .Lgu_tnext
; __device__ void phase_gather_u(const Params& p) {
;     ...
; #pragma unroll
;         for (int k = 0; k < 16; ++k) {
;           int j = jfirst, e = efirst;
;           if (m0) { const int jj = __builtin_amdgcn_readfirstlane(__ffsll((long long)m0) - 1); m0 &= m0 - 1ull; j = jj; e = __builtin_amdgcn_readlane(idA, jj); }
;           else if (m1) { const int jj = __builtin_amdgcn_readfirstlane(__ffsll((long long)m1) - 1); m1 &= m1 - 1ull; j = 64 + jj; e = __builtin_amdgcn_readlane(idB, jj); }
;           jk[k] = j;
;           rw[k] = *(const u32x4*)(ub + (size_t)e * 1024 + lane * 16);
;         }
; #pragma unroll
;         for (int bt = 0; bt < 2; ++bt) {
;           int dv[8];
; #pragma unroll
;           for (int k = 0; k < 8; ++k) {
;             int dh = 0, dl = 0;
; #pragma unroll
;             for (int q = 0; q < 4; ++q) {
;               dh = __builtin_amdgcn_sdot8((int)rw[bt * 8 + k][q], (int)ph[q], dh, false);
;               dl = __builtin_amdgcn_sdot8((int)rw[bt * 8 + k][q], (int)pl[q], dl, false);
;             }
;             dv[k] = 16 * dh + dl;
;           }
;           int a4[4], a2[2];
; #pragma unroll
;           for (int k = 0; k < 4; ++k) {
;             const int mine = b5 ? dv[k + 4] : dv[k], oth = b5 ? dv[k] : dv[k + 4];
;             a4[k] = mine + __shfl_xor(oth, 32);
;           }
; #pragma unroll
;           for (int k = 0; k < 2; ++k) {
;             const int mine = b4 ? a4[k + 2] : a4[k], oth = b4 ? a4[k] : a4[k + 2];
;             a2[k] = mine + __shfl_xor(oth, 16);
;           }
;           int c1;
;           {
;             const int mine = b3 ? a2[1] : a2[0], oth = b3 ? a2[0] : a2[1];
;             c1 = mine + __shfl_xor(oth, 8);
;           }
;           c1 += __shfl_xor(c1, 4);
;           c1 += __shfl_xor(c1, 2);
;           c1 += __shfl_xor(c1, 1);
;           const int val = __shfl(c1, srcl);
;           int jsel = jk[bt * 8];
; #pragma unroll
;           for (int k = 1; k < 8; ++k) jsel = (lane == k) ? jk[bt * 8 + k] : jsel;
;           if (lane < 8 && lane < nvalid - bt * 8) wbuf[(size_t)t * 128 + jsel] = val;
;         }
;       }
;     }
	s_waitcnt lgkmcnt(0)
	v_mov_b32_e32 v103, v115
	ds_read_b32 v115, v101
	v_cmp_gt_u32_e64 s[52:53], s56, v102
	v_add_u32_e32 v101, 16, v101
	v_add_u32_e32 v102, 4, v102
	s_nop 0
	v_cndmask_b32_e64 v103, 0, v103, s[52:53]
	v_and_b32_e32 v104, 0xffffff00, v103
	v_and_b32_e32 v106, 0xff, v103
	v_lshl_add_u32 v104, v104, 2, v96
	v_lshlrev_b32_e32 v106, 2, v106
	s_and_b64 s[52:53], s[52:53], s[8:9]
	global_load_dwordx4 v[48:51], v104, s[34:35]
	global_load_dwordx4 v[52:55], v104, s[34:35] offset:256
	global_load_dwordx4 v[56:59], v104, s[34:35] offset:512
	global_load_dwordx4 v[60:63], v104, s[34:35] offset:768
	s_waitcnt vmcnt(8)
	v_mov_b32_e32 v108, 0
	v_mov_b32_e32 v109, 0
	s_nop 1
	v_dot8c_i32_i4_e32 v108, v144, v0
	v_dot8c_i32_i4_e32 v109, v144, v4
	v_dot8c_i32_i4_e32 v108, v145, v1
	v_dot8c_i32_i4_e32 v109, v145, v5
	v_dot8c_i32_i4_e32 v108, v146, v2
	v_dot8c_i32_i4_e32 v109, v146, v6
	v_dot8c_i32_i4_e32 v108, v147, v3
	v_dot8c_i32_i4_e32 v109, v147, v7
	v_dot8c_i32_i4_e32 v108, v148, v8
	v_dot8c_i32_i4_e32 v109, v148, v12
	v_dot8c_i32_i4_e32 v108, v149, v9
	v_dot8c_i32_i4_e32 v109, v149, v13
	v_dot8c_i32_i4_e32 v108, v150, v10
	v_dot8c_i32_i4_e32 v109, v150, v14
	v_dot8c_i32_i4_e32 v108, v151, v11
	v_dot8c_i32_i4_e32 v109, v151, v15
	v_dot8c_i32_i4_e32 v108, v152, v16
	v_dot8c_i32_i4_e32 v109, v152, v20
	v_dot8c_i32_i4_e32 v108, v153, v17
	v_dot8c_i32_i4_e32 v109, v153, v21
	v_dot8c_i32_i4_e32 v108, v154, v18
	v_dot8c_i32_i4_e32 v109, v154, v22
	v_dot8c_i32_i4_e32 v108, v155, v19
	v_dot8c_i32_i4_e32 v109, v155, v23
	v_dot8c_i32_i4_e32 v108, v156, v24
	v_dot8c_i32_i4_e32 v109, v156, v28
	v_dot8c_i32_i4_e32 v108, v157, v25
	v_dot8c_i32_i4_e32 v109, v157, v29
	v_dot8c_i32_i4_e32 v108, v158, v26
	v_dot8c_i32_i4_e32 v109, v158, v30
	v_dot8c_i32_i4_e32 v108, v159, v27
	v_dot8c_i32_i4_e32 v109, v159, v31
	s_nop 2
	v_lshl_add_u32 v110, v108, 4, v109
	s_nop 1
	v_add_u32_dpp v110, v110, v110 quad_perm:[1,0,3,2] row_mask:0xf bank_mask:0xf
	s_nop 1
	v_add_u32_dpp v110, v110, v110 quad_perm:[2,3,0,1] row_mask:0xf bank_mask:0xf
	s_nop 1
	v_add_u32_dpp v110, v110, v110 row_half_mirror row_mask:0xf bank_mask:0xf
	s_nop 1
	v_add_u32_dpp v110, v110, v110 row_mirror row_mask:0xf bank_mask:0xf
	s_mov_b64 exec, s[54:55]
	global_store_dword v107, v110, s[48:49]
	s_mov_b64 exec, -1
	s_add_i32 s58, s58, 1
	s_cmp_lt_u32 s58, s57
	s_cbranch_scc1 .Lgu_gloop
.Lgu_tnext:
	s_add_i32 s36, s36, s68
	s_cmp_le_i32 s36, 0x3fff
	s_cbranch_scc1 .Lgu_tloop
	s_add_i32 s33, s33, 1
	s_cmp_lt_u32 s33, 4
	s_cbranch_scc1 .Lgu_rloop
.Lgu_done:
	s_or_b64 exec, exec, s[38:39]
	s_waitcnt vmcnt(0) lgkmcnt(0)
